# attention: online-softmax rescale only when a row max grows by more than 8 (lazy rescale, exact softmax)
# speedup vs baseline: 1.0965x; 1.0085x over previous
.LBB0_885:
	ds_read_b128 v[34:37], v172
	ds_read_b128 v[38:41], v172 offset:32
	ds_read_b128 v[42:45], v172 offset:64
	ds_read_b128 v[46:49], v172 offset:96
	ds_read_b128 v[98:101], v172 offset:4608
	ds_read_b128 v[102:105], v172 offset:4640
	ds_read_b128 v[106:109], v172 offset:4672
	ds_read_b128 v[110:113], v172 offset:4704
	s_waitcnt vmcnt(5) lgkmcnt(7)
	v_mfma_f32_32x32x16_bf16 v[50:65], v[34:37], v[66:69], 0
	v_add_u32_e32 v0, 0x2000, v173
	ds_read2_b64 v[126:129], v0 offset0:128 offset1:130
	ds_read2_b64 v[114:117], v0 offset0:132 offset1:134
	s_waitcnt vmcnt(4) lgkmcnt(8)
	v_mfma_f32_32x32x16_bf16 v[50:65], v[38:41], v[70:73], v[50:65]
	s_waitcnt vmcnt(1) lgkmcnt(7)
	v_mfma_f32_32x32x16_bf16 v[50:65], v[42:45], v[78:81], v[50:65]
	s_waitcnt vmcnt(0) lgkmcnt(6)
	v_mfma_f32_32x32x16_bf16 v[50:65], v[46:49], v[82:85], v[50:65]
	s_waitcnt lgkmcnt(5)
	v_mfma_f32_32x32x16_bf16 v[34:49], v[98:101], v[66:69], 0
	v_add_u32_e32 v98, 0x3000, v173
	s_waitcnt lgkmcnt(4)
	v_mfma_f32_32x32x16_bf16 v[34:49], v[102:105], v[70:73], v[34:49]
	s_waitcnt lgkmcnt(3)
	v_mfma_f32_32x32x16_bf16 v[34:49], v[106:109], v[78:81], v[34:49]
	s_waitcnt lgkmcnt(2)
	v_mfma_f32_32x32x16_bf16 v[34:49], v[110:113], v[82:85], v[34:49]
	ds_read2_b64 v[122:125], v98 offset0:160 offset1:162
	ds_read2_b64 v[118:121], v98 offset0:164 offset1:166
	ds_read2_b64 v[110:113], v0 offset0:136 offset1:138
	ds_read2_b64 v[106:109], v98 offset0:168 offset1:170
	ds_read2_b64 v[102:105], v0 offset0:140 offset1:142
	ds_read2_b64 v[98:101], v98 offset0:172 offset1:174
	v_max_f32_e32 v0, v51, v51
	v_max_f32_e32 v174, v50, v50
	v_max_f32_e32 v0, v174, v0
	v_max3_f32 v0, v0, v52, v53
	v_max3_f32 v0, v0, v54, v55
	v_max3_f32 v0, v0, v56, v57
	v_max3_f32 v0, v0, v58, v59
	v_max3_f32 v0, v0, v60, v61
	v_max3_f32 v0, v0, v62, v63
	v_max3_f32 v0, v0, v64, v65
	v_max3_f32 v0, v0, v34, v35
	v_max3_f32 v0, v0, v36, v37
	v_max3_f32 v0, v0, v38, v39
	v_max3_f32 v0, v0, v40, v41
	v_max3_f32 v0, v0, v42, v43
	v_max3_f32 v0, v0, v44, v45
	v_max3_f32 v0, v0, v46, v47
	v_max3_f32 v0, v0, v48, v49
	ds_bpermute_b32 v174, v170, v0
	s_waitcnt lgkmcnt(0)
	v_max_f32_e32 v174, v174, v174
	v_max_f32_e32 v0, v0, v174
	v_add_f32_e32 v174, 0x41000000, v151
	v_cmp_gt_f32_e32 vcc, v0, v174
	s_cbranch_vccz .LBB0_887
	v_max_f32_e32 v0, v0, v0
	v_max_f32_e32 v174, v151, v151
	v_max_f32_e32 v174, v174, v0
	v_sub_f32_e32 v0, v151, v174
	v_exp_f32_e32 v0, v0
	v_mov_b32_e32 v151, v174
	v_mul_f32_e32 v153, v153, v0
	v_mul_f32_e32 v32, v32, v0
	v_mul_f32_e32 v33, v33, v0
	v_mul_f32_e32 v30, v30, v0
	v_mul_f32_e32 v31, v31, v0
	v_mul_f32_e32 v28, v28, v0
	v_mul_f32_e32 v29, v29, v0
	v_mul_f32_e32 v26, v26, v0
	v_mul_f32_e32 v27, v27, v0
	v_mul_f32_e32 v24, v24, v0
	v_mul_f32_e32 v25, v25, v0
	v_mul_f32_e32 v22, v22, v0
	v_mul_f32_e32 v23, v23, v0
	v_mul_f32_e32 v20, v20, v0
	v_mul_f32_e32 v21, v21, v0
	v_mul_f32_e32 v18, v18, v0
	v_mul_f32_e32 v19, v19, v0
	v_mul_f32_e32 v16, v16, v0
	v_mul_f32_e32 v17, v17, v0
	v_mul_f32_e32 v14, v14, v0
	v_mul_f32_e32 v15, v15, v0
	v_mul_f32_e32 v12, v12, v0
	v_mul_f32_e32 v13, v13, v0
	v_mul_f32_e32 v10, v10, v0
	v_mul_f32_e32 v11, v11, v0
	v_mul_f32_e32 v8, v8, v0
	v_mul_f32_e32 v9, v9, v0
	v_mul_f32_e32 v6, v6, v0
	v_mul_f32_e32 v7, v7, v0
	v_mul_f32_e32 v4, v4, v0
	v_mul_f32_e32 v5, v5, v0
	v_mul_f32_e32 v2, v2, v0
	v_mul_f32_e32 v3, v3, v0

.LBB0_889:
	v_add_f32_e32 v0, 0, v0
	v_add_f32_e32 v0, v50, v0
	v_add_f32_e32 v0, v51, v0
	v_add_f32_e32 v0, v52, v0
	v_add_f32_e32 v0, v53, v0
	v_add_f32_e32 v0, v54, v0
	v_add_f32_e32 v0, v55, v0
	v_add_f32_e32 v0, v56, v0
	v_add_f32_e32 v0, v57, v0
	v_add_f32_e32 v0, v58, v0
	v_add_f32_e32 v0, v59, v0
	v_add_f32_e32 v0, v60, v0
	v_add_f32_e32 v0, v61, v0
	v_add_f32_e32 v0, v62, v0
	v_add_f32_e32 v0, v63, v0
	v_add_f32_e32 v0, v64, v0
	v_add_f32_e32 v0, v34, v0
	v_add_f32_e32 v0, v35, v0
	v_add_f32_e32 v0, v36, v0
	v_add_f32_e32 v0, v37, v0
	v_add_f32_e32 v0, v38, v0
	v_add_f32_e32 v0, v39, v0
	v_add_f32_e32 v0, v40, v0
	v_add_f32_e32 v0, v41, v0
	v_add_f32_e32 v0, v42, v0
	v_add_f32_e32 v0, v43, v0
	v_add_f32_e32 v0, v44, v0
	v_add_f32_e32 v0, v45, v0
	v_add_f32_e32 v0, v46, v0
	v_add_f32_e32 v0, v47, v0
	v_add_f32_e32 v0, v48, v0
	v_add_f32_e32 v0, v49, v0
	ds_read_b128 v[34:37], v172 offset:17920
	ds_read_b128 v[38:41], v172 offset:17952
	ds_read_b128 v[42:45], v172 offset:17984
	ds_read_b128 v[46:49], v172 offset:18016
	ds_read_b128 v[98:101], v172 offset:22528
	ds_read_b128 v[102:105], v172 offset:22560
	ds_read_b128 v[106:109], v172 offset:22592
	ds_read_b128 v[110:113], v172 offset:22624
	v_add_f32_e32 v0, v153, v0
	s_waitcnt lgkmcnt(7)
	v_mfma_f32_32x32x16_bf16 v[50:65], v[34:37], v[66:69], 0
	s_waitcnt lgkmcnt(6)
	v_mfma_f32_32x32x16_bf16 v[50:65], v[38:41], v[70:73], v[50:65]
	s_waitcnt lgkmcnt(5)
	v_mfma_f32_32x32x16_bf16 v[50:65], v[42:45], v[78:81], v[50:65]
	s_waitcnt lgkmcnt(4)
	v_mfma_f32_32x32x16_bf16 v[50:65], v[46:49], v[82:85], v[50:65]
	s_waitcnt lgkmcnt(3)
	v_mfma_f32_32x32x16_bf16 v[34:49], v[98:101], v[66:69], 0
	v_add_u32_e32 v98, 0x6800, v173
	v_add_u32_e32 v99, 0x7800, v173
	ds_read2_b64 v[126:129], v98 offset0:64 offset1:66
	ds_read2_b64 v[114:117], v98 offset0:68 offset1:70
	s_waitcnt lgkmcnt(4)
	v_mfma_f32_32x32x16_bf16 v[34:49], v[102:105], v[70:73], v[34:49]
	s_waitcnt lgkmcnt(3)
	v_mfma_f32_32x32x16_bf16 v[34:49], v[106:109], v[78:81], v[34:49]
	s_waitcnt lgkmcnt(2)
	v_mfma_f32_32x32x16_bf16 v[34:49], v[110:113], v[82:85], v[34:49]
	ds_read2_b64 v[122:125], v99 offset0:96 offset1:98
	ds_read2_b64 v[118:121], v99 offset0:100 offset1:102
	ds_read2_b64 v[110:113], v98 offset0:72 offset1:74
	ds_read2_b64 v[106:109], v99 offset0:104 offset1:106
	ds_read2_b64 v[102:105], v98 offset0:76 offset1:78
	ds_read2_b64 v[98:101], v99 offset0:108 offset1:110
	v_max_f32_e32 v153, v51, v51
	v_max_f32_e32 v162, v50, v50
	v_max_f32_e32 v153, v162, v153
	v_max3_f32 v153, v153, v52, v53
	v_max3_f32 v153, v153, v54, v55
	v_max3_f32 v153, v153, v56, v57
	v_max3_f32 v153, v153, v58, v59
	v_max3_f32 v153, v153, v60, v61
	v_max3_f32 v153, v153, v62, v63
	v_max3_f32 v153, v153, v64, v65
	v_max3_f32 v153, v153, v34, v35
	v_max3_f32 v153, v153, v36, v37
	v_max3_f32 v153, v153, v38, v39
	v_max3_f32 v153, v153, v40, v41
	v_max3_f32 v153, v153, v42, v43
	v_max3_f32 v153, v153, v44, v45
	v_max3_f32 v153, v153, v46, v47
	v_max3_f32 v153, v153, v48, v49
	ds_bpermute_b32 v162, v170, v153
	s_waitcnt lgkmcnt(0)
	v_max_f32_e32 v162, v162, v162
	v_max_f32_e32 v153, v153, v162
	v_add_f32_e32 v162, 0x41000000, v151
	v_cmp_gt_f32_e32 vcc, v153, v162
	s_cbranch_vccz .LBB0_891
	v_max_f32_e32 v153, v153, v153
	v_max_f32_e32 v162, v151, v151
	v_max_f32_e32 v153, v162, v153
	v_sub_f32_e32 v151, v151, v153
	v_exp_f32_e32 v162, v151
	v_mov_b32_e32 v151, v153
	v_mul_f32_e32 v0, v0, v162
	v_mul_f32_e32 v32, v32, v162
	v_mul_f32_e32 v33, v33, v162
	v_mul_f32_e32 v30, v30, v162
	v_mul_f32_e32 v31, v31, v162
	v_mul_f32_e32 v28, v28, v162
	v_mul_f32_e32 v29, v29, v162
	v_mul_f32_e32 v26, v26, v162
	v_mul_f32_e32 v27, v27, v162
	v_mul_f32_e32 v24, v24, v162
	v_mul_f32_e32 v25, v25, v162
	v_mul_f32_e32 v22, v22, v162
	v_mul_f32_e32 v23, v23, v162
	v_mul_f32_e32 v20, v20, v162
	v_mul_f32_e32 v21, v21, v162
	v_mul_f32_e32 v18, v18, v162
	v_mul_f32_e32 v19, v19, v162
	v_mul_f32_e32 v16, v16, v162
	v_mul_f32_e32 v17, v17, v162
	v_mul_f32_e32 v14, v14, v162
	v_mul_f32_e32 v15, v15, v162
	v_mul_f32_e32 v12, v12, v162
	v_mul_f32_e32 v13, v13, v162
	v_mul_f32_e32 v10, v10, v162
	v_mul_f32_e32 v11, v11, v162
	v_mul_f32_e32 v8, v8, v162
	v_mul_f32_e32 v9, v9, v162
	v_mul_f32_e32 v6, v6, v162
	v_mul_f32_e32 v7, v7, v162
	v_mul_f32_e32 v4, v4, v162
	v_mul_f32_e32 v5, v5, v162
	v_mul_f32_e32 v2, v2, v162
	v_mul_f32_e32 v3, v3, v162
